# sample-attention key norms computed in transposed MFMA form (keys along lanes: in-lane sum of squares + two v_permlane swaps replace 16-lane DPP reductions); prompt-attn unmasked fast path; waves 4-7
# speedup vs baseline: 1.0288x; 1.0088x over previous
; #define LAS __attribute__((address_space(3)))
; DI void attn_sample_phase(const Args& a, LAS unsigned char* lds, int vcu, int G, int tid, int lane, int wave) {
;     ...
;             { const LAS unsigned char* c8b = C8 + (j & 1) * 8704; const LAS float* spe = SSPE + (j & 1) * 32;
; #pragma unroll
;                 for (int kb = 0; kb < 2; ++kb) { f32x4 acc[4] = {};
; #pragma unroll
;                     for (int ks = 0; ks < 2; ++ks) { const LAS unsigned char* ap = c8b + (kb * 16 + r16) * 272 + 128 * ks + 32 * q4;
;                         const u32x4 x0 = *(const LAS u32x4*)ap, x1 = *(const LAS u32x4*)(ap + 16);
;                         const v8i_t af = {(int)x0.x, (int)x0.y, (int)x0.z, (int)x0.w, (int)x1.x, (int)x1.y, (int)x1.z, (int)x1.w};
; #pragma unroll
;                         for (int nb = 0; nb < 4; ++nb) acc[nb] = __builtin_amdgcn_mfma_scale_f32_16x16x128_f8f6f4(af, wf8[nb][ks], acc[nb], 0, 0, 0, 0x7F7F7F7F, 0, 0x7F7F7F7F); }
;                     f32x4 sq = (acc[0] * acc[0] + acc[1] * acc[1] + acc[2] * acc[2] + acc[3] * acc[3]) * (1.f / 256.f);
;                     sq.x = row16_sum(sq.x); sq.y = row16_sum(sq.y); sq.z = row16_sum(sq.z); sq.w = row16_sum(sq.w);
;                     if (r16 == 0) { const f32x4 pe = *(const LAS f32x4*)(spe + kb * 16 + 4 * q4); f32x4 r;
;                         r.x = __builtin_amdgcn_rsqf((sq.x + pe.x) * (1.f / 96.f) + EPS); r.y = __builtin_amdgcn_rsqf((sq.y + pe.y) * (1.f / 96.f) + EPS);
;                         r.z = __builtin_amdgcn_rsqf((sq.z + pe.z) * (1.f / 96.f) + EPS); r.w = __builtin_amdgcn_rsqf((sq.w + pe.w) * (1.f / 96.f) + EPS);
;                         *(LAS f32x4*)(RI + wave * 32 + kb * 16 + 4 * q4) = r; } } }
.LBB0_904:
	s_add_i32 s26, s25, -2
	s_and_b32 s8, s26, 1
	s_mul_i32 s9, s8, 0x2200
	v_add_u32_e32 v2, s9, v202
	s_lshl_b32 s8, s8, 7
	v_lshl_add_u32 v254, v140, 2, s8
	v_add_u32_e32 v254, 0x17a00, v254
	ds_read_b128 v[212:215], v2 offset:56832
	ds_read_b128 v[216:219], v2 offset:56848
	ds_read_b128 v[236:239], v2 offset:56960
	ds_read_b128 v[240:243], v2 offset:56976
	ds_read_b128 v[246:249], v2 offset:61184
	ds_read_b128 v[250:253], v2 offset:61200
	ds_read_b32 v232, v254
	ds_read_b32 v233, v254 offset:64
	v_lshlrev_b32_e32 v255, 7, v158
	v_lshl_add_u32 v255, v140, 2, v255
	v_add_u32_e32 v255, 0x17600, v255
	s_mov_b64 s[100:101], 0xffff
	s_waitcnt lgkmcnt(6)
	v_mfma_scale_f32_16x16x128_f8f6f4 v[220:223], v[36:43], v[212:219], 0, v208, v208 op_sel_hi:[0,0,0]
	s_waitcnt lgkmcnt(4)
	v_mfma_scale_f32_16x16x128_f8f6f4 v[220:223], v[44:51], v[236:243], v[220:223], v208, v208 op_sel_hi:[0,0,0]
	v_mfma_scale_f32_16x16x128_f8f6f4 v[136:139], v[20:27], v[212:219], 0, v208, v208 op_sel_hi:[0,0,0]
	v_mfma_scale_f32_16x16x128_f8f6f4 v[136:139], v[28:35], v[236:243], v[136:139], v208, v208 op_sel_hi:[0,0,0]
	v_mfma_scale_f32_16x16x128_f8f6f4 v[224:227], v[52:59], v[212:219], 0, v208, v208 op_sel_hi:[0,0,0]
	v_mfma_scale_f32_16x16x128_f8f6f4 v[224:227], v[60:67], v[236:243], v[224:227], v208, v208 op_sel_hi:[0,0,0]
	v_mfma_scale_f32_16x16x128_f8f6f4 v[228:231], v[68:75], v[212:219], 0, v208, v208 op_sel_hi:[0,0,0]
	v_mfma_scale_f32_16x16x128_f8f6f4 v[228:231], v[76:83], v[236:243], v[228:231], v208, v208 op_sel_hi:[0,0,0]
	ds_read_b128 v[212:215], v2 offset:61312
	ds_read_b128 v[216:219], v2 offset:61328
	s_nop 3
	v_mul_f32_e32 v234, v220, v220
	v_fmac_f32_e32 v234, v221, v221
	v_fmac_f32_e32 v234, v222, v222
	v_fmac_f32_e32 v234, v223, v223
	v_fmac_f32_e32 v234, v136, v136
	v_fmac_f32_e32 v234, v137, v137
	v_fmac_f32_e32 v234, v138, v138
	v_fmac_f32_e32 v234, v139, v139
	v_fmac_f32_e32 v234, v224, v224
	v_fmac_f32_e32 v234, v225, v225
	v_fmac_f32_e32 v234, v226, v226
	v_fmac_f32_e32 v234, v227, v227
	v_fmac_f32_e32 v234, v228, v228
	v_fmac_f32_e32 v234, v229, v229
	v_fmac_f32_e32 v234, v230, v230
	v_fmac_f32_e32 v234, v231, v231
	s_waitcnt lgkmcnt(0)
	v_mfma_scale_f32_16x16x128_f8f6f4 v[220:223], v[36:43], v[246:253], 0, v208, v208 op_sel_hi:[0,0,0]
	v_mov_b32_e32 v235, v234
	s_nop 1
	v_mfma_scale_f32_16x16x128_f8f6f4 v[220:223], v[44:51], v[212:219], v[220:223], v208, v208 op_sel_hi:[0,0,0]
	v_permlane32_swap_b32_e32 v235, v234
	v_add_f32_e32 v234, v234, v235
	v_mfma_scale_f32_16x16x128_f8f6f4 v[224:227], v[20:27], v[246:253], 0, v208, v208 op_sel_hi:[0,0,0]
	v_mov_b32_e32 v235, v234
	s_nop 1
	v_mfma_scale_f32_16x16x128_f8f6f4 v[224:227], v[28:35], v[212:219], v[224:227], v208, v208 op_sel_hi:[0,0,0]
	v_permlane16_swap_b32_e32 v235, v234
	v_add_f32_e32 v234, v234, v235
	v_mfma_scale_f32_16x16x128_f8f6f4 v[228:231], v[52:59], v[246:253], 0, v208, v208 op_sel_hi:[0,0,0]
	v_fmamk_f32 v234, v234, 0x3b800000, v232
	v_fmamk_f32 v234, v234, 0x3c2aaaab, v209
	v_mfma_scale_f32_16x16x128_f8f6f4 v[228:231], v[60:67], v[212:219], v[228:231], v208, v208 op_sel_hi:[0,0,0]
	v_rsq_f32_e32 v234, v234
	v_mfma_scale_f32_16x16x128_f8f6f4 v[136:139], v[68:75], v[246:253], 0, v208, v208 op_sel_hi:[0,0,0]
	v_mfma_scale_f32_16x16x128_f8f6f4 v[136:139], v[76:83], v[212:219], v[136:139], v208, v208 op_sel_hi:[0,0,0]
	s_and_saveexec_b64 s[18:19], s[100:101]
	ds_write_b32 v255, v234
	s_or_b64 exec, exec, s[18:19]
	v_mul_f32_e32 v234, v220, v220
	v_fmac_f32_e32 v234, v221, v221
	v_fmac_f32_e32 v234, v222, v222
	v_fmac_f32_e32 v234, v223, v223
	v_fmac_f32_e32 v234, v224, v224
	v_fmac_f32_e32 v234, v225, v225
	v_fmac_f32_e32 v234, v226, v226
	v_fmac_f32_e32 v234, v227, v227
	v_fmac_f32_e32 v234, v228, v228
	v_fmac_f32_e32 v234, v229, v229
	v_fmac_f32_e32 v234, v230, v230
	v_fmac_f32_e32 v234, v231, v231
	v_fmac_f32_e32 v234, v136, v136
	v_fmac_f32_e32 v234, v137, v137
	v_fmac_f32_e32 v234, v138, v138
	v_fmac_f32_e32 v234, v139, v139
	v_mov_b32_e32 v235, v234
	s_nop 1
	v_permlane32_swap_b32_e32 v235, v234
	v_add_f32_e32 v234, v234, v235
	v_mov_b32_e32 v235, v234
	s_nop 1
	v_permlane16_swap_b32_e32 v235, v234
	v_add_f32_e32 v234, v234, v235
	v_fmamk_f32 v234, v234, 0x3b800000, v233
	v_fmamk_f32 v234, v234, 0x3c2aaaab, v209
	v_rsq_f32_e32 v234, v234
	s_and_saveexec_b64 s[18:19], s[100:101]
	ds_write_b32 v255, v234 offset:64
	s_or_b64 exec, exec, s[18:19]

; __global__ void __launch_bounds__(NTHR, 2) mega_fwd(Args args) {
	.amdhsa_kernel _Z8mega_fwd4Args
		.amdhsa_group_segment_fixed_size 0
		.amdhsa_private_segment_fixed_size 0
		.amdhsa_kernarg_size 584
		.amdhsa_user_sgpr_count 2
		.amdhsa_user_sgpr_dispatch_ptr 0
		.amdhsa_user_sgpr_queue_ptr 0
		.amdhsa_user_sgpr_kernarg_segment_ptr 1
		.amdhsa_user_sgpr_dispatch_id 0
		.amdhsa_user_sgpr_kernarg_preload_length 0
		.amdhsa_user_sgpr_kernarg_preload_offset 0
		.amdhsa_user_sgpr_private_segment_size 0
		.amdhsa_uses_dynamic_stack 0
		.amdhsa_enable_private_segment 0
		.amdhsa_system_sgpr_workgroup_id_x 1
		.amdhsa_system_sgpr_workgroup_id_y 0
		.amdhsa_system_sgpr_workgroup_id_z 0
		.amdhsa_system_sgpr_workgroup_info 0
		.amdhsa_system_vgpr_workitem_id 0
		.amdhsa_next_free_vgpr 256
		.amdhsa_next_free_sgpr 102
		.amdhsa_accum_offset 256
		.amdhsa_reserve_vcc 1
		.amdhsa_float_round_mode_32 0
		.amdhsa_float_round_mode_16_64 0
		.amdhsa_float_denorm_mode_32 3
		.amdhsa_float_denorm_mode_16_64 3
		.amdhsa_dx10_clamp 1
		.amdhsa_ieee_mode 1
		.amdhsa_fp16_overflow 0
		.amdhsa_tg_split 0
		.amdhsa_exception_fp_ieee_invalid_op 0
		.amdhsa_exception_fp_denorm_src 0
		.amdhsa_exception_fp_ieee_div_zero 0
		.amdhsa_exception_fp_ieee_overflow 0
		.amdhsa_exception_fp_ieee_underflow 0
		.amdhsa_exception_fp_ieee_inexact 0
		.amdhsa_exception_int_div_zero 0
	.end_amdhsa_kernel

; __global__ void __launch_bounds__(NTHR, 2) mega_fwd(Args args) {
amdhsa.kernels:
  - .agpr_count:     0
    .args:
      - .offset:         0
        .size:           328
        .value_kind:     by_value
      - .offset:         328
        .size:           4
        .value_kind:     hidden_block_count_x
      - .offset:         332
        .size:           4
        .value_kind:     hidden_block_count_y
      - .offset:         336
        .size:           4
        .value_kind:     hidden_block_count_z
      - .offset:         340
        .size:           2
        .value_kind:     hidden_group_size_x
      - .offset:         342
        .size:           2
        .value_kind:     hidden_group_size_y
      - .offset:         344
        .size:           2
        .value_kind:     hidden_group_size_z
      - .offset:         346
        .size:           2
        .value_kind:     hidden_remainder_x
      - .offset:         348
        .size:           2
        .value_kind:     hidden_remainder_y
      - .offset:         350
        .size:           2
        .value_kind:     hidden_remainder_z
      - .offset:         368
        .size:           8
        .value_kind:     hidden_global_offset_x
      - .offset:         376
        .size:           8
        .value_kind:     hidden_global_offset_y
      - .offset:         384
        .size:           8
        .value_kind:     hidden_global_offset_z
      - .offset:         392
        .size:           2
        .value_kind:     hidden_grid_dims
      - .offset:         448
        .size:           4
        .value_kind:     hidden_dynamic_lds_size
    .group_segment_fixed_size: 0
    .kernarg_segment_align: 8
    .kernarg_segment_size: 584
    .language:       OpenCL C
    .language_version:
      - 2
      - 0
    .max_flat_workgroup_size: 512
    .name:           _Z8mega_fwd4Args
    .private_segment_fixed_size: 0
    .sgpr_count:     108
    .sgpr_spill_count: 85
    .symbol:         _Z8mega_fwd4Args.kd
    .uniform_work_group_size: 1
    .uses_dynamic_stack: false
    .vgpr_count:     256
    .vgpr_spill_count: 0
    .wavefront_size: 64
